# mixer queue: next unit index fetched at the start of the FoX/SB epilogue (pop-ahead), pop only publishes it
# baseline (speedup 1.0000x reference)
.LBB0_25:
	v_mov_b32_e32 v182, v212
	s_mov_b32 s94, s60
	s_cmp_lg_u32 s60, 0
	s_mov_b64 s[0:1], -1
	s_movk_i32 s60, 0x800
	s_cbranch_scc0 .LBB0_939
	s_add_i32 s0, s94, -1
	s_mul_hi_i32 s1, s0, 0x55555556
	s_lshr_b32 s4, s1, 31
	s_add_i32 s16, s1, s4
	s_mul_i32 s1, s16, 3
	s_sub_i32 s62, s0, s1
	s_mov_b32 s7, s61
	s_mov_b64 s[4:5], -1
	s_cmp_lt_i32 s62, 1
	s_mov_b64 s[0:1], 0
	v_writelane_b32 v250, s6, 7
	s_nop 1
	v_writelane_b32 v250, s7, 8
	s_cbranch_scc1 .LBB0_285
	s_cmp_eq_u32 s62, 1
	s_mov_b64 s[0:1], -1
	s_cbranch_scc0 .LBB0_289
	s_ashr_i32 s17, s16, 31
	s_lshl_b64 s[0:1], s[16:17], 2
	v_readlane_b32 s4, v252, 0
	v_readlane_b32 s5, v252, 1
	s_add_u32 s4, s4, s0
	s_addc_u32 s5, s5, s1
	v_writelane_b32 v250, s4, 11
	s_add_i32 s6, s16, 1
	s_cmp_lt_i32 s94, 10
	v_writelane_b32 v250, s5, 12
	s_movk_i32 s4, 0x388
	s_mul_i32 s8, s16, 0x280
	s_cselect_b32 s69, s4, 0x340
	s_add_i32 s10, s8, 0x140
	s_lshl_b32 s18, s16, 2
	v_writelane_b32 v250, s94, 13
	s_ashr_i32 s11, s10, 31
	s_ashr_i32 s19, s18, 31
	s_ashr_i32 s7, s6, 31
	s_lshl_b32 s4, s6, 10
	s_lshl_b32 s5, s6, 6
	s_lshl_b32 s24, s6, 8
	s_ashr_i32 s9, s8, 31
	s_lshl_b64 s[20:21], s[18:19], 13
	s_mov_b64 s[38:39], s[96:97]
	s_lshl_b64 s[96:97], s[6:7], 10
	s_lshl_b64 s[12:13], s[6:7], 15
	v_writelane_b32 v250, s5, 14
	s_ashr_i32 s25, s24, 31
	s_ashr_i32 s5, s4, 31
	s_lshl_b64 s[10:11], s[10:11], 2
	s_add_u32 s22, s93, s10
	s_addc_u32 s23, s92, s11
	s_lshl_b64 s[8:9], s[8:9], 2
	s_mov_b64 s[40:41], s[16:17]
	s_add_u32 s16, s93, s8
	s_addc_u32 s17, s92, s9
	s_add_u32 s8, s70, s0
	s_addc_u32 s9, s71, s1
	s_add_u32 s0, s8, 0x7e00
	s_mul_i32 s34, s6, 0x700000
	s_addc_u32 s1, s9, 0
	s_mul_hi_i32 s19, s6, 0x700000
	v_writelane_b32 v250, s0, 15
	s_add_u32 s94, s66, s34
	s_addc_u32 s95, s67, s19
	v_writelane_b32 v250, s1, 16
	s_lshl_b64 s[0:1], s[6:7], 21
	s_add_u32 s0, s38, s0
	s_addc_u32 s1, s39, s1
	v_readlane_b32 s10, v252, 6
	v_readlane_b32 s11, v252, 7
	s_add_u32 s12, s10, s12
	s_addc_u32 s13, s11, s13
	v_writelane_b32 v250, s12, 17
	s_add_u32 s8, s8, 0x7e04
	s_addc_u32 s9, s9, 0
	v_writelane_b32 v250, s13, 18
	v_writelane_b32 v250, s8, 19
	s_mul_hi_i32 s36, s6, 0xe08000
	s_mul_i32 s37, s6, 0xe08000
	v_writelane_b32 v250, s9, 20
	s_lshl_b64 s[8:9], s[24:25], 2
	s_add_u32 s8, s86, s8
	s_addc_u32 s9, s87, s9
	s_lshl_b64 s[6:7], s[6:7], 22
	s_add_u32 s12, s88, s6
	s_addc_u32 s13, s89, s7
	v_writelane_b32 v250, s8, 21
	s_add_u32 s6, s76, s37
	s_addc_u32 s7, s77, s36
	v_writelane_b32 v250, s9, 22
	s_lshl_b64 s[8:9], s[4:5], 2
	s_add_u32 s8, s74, s8
	s_addc_u32 s9, s75, s9
	s_add_u32 s10, s10, s20
	s_addc_u32 s11, s11, s21
	v_writelane_b32 v250, s10, 23
	v_readlane_b32 s5, v251, 39
	s_mov_b64 s[66:67], 0
	v_writelane_b32 v250, s11, 24
	s_add_u32 s10, s5, s20
	v_readlane_b32 s5, v251, 40
	s_addc_u32 s11, s5, s21
	v_writelane_b32 v250, s10, 25
	v_readlane_b32 s5, v251, 41
	s_mov_b64 s[92:93], 0
	v_writelane_b32 v250, s11, 26
	s_add_u32 s10, s5, s20
	v_readlane_b32 s5, v251, 42
	s_addc_u32 s11, s5, s21
	v_writelane_b32 v250, s10, 27
	v_readlane_b32 s5, v251, 43
	v_mov_b32_e32 v128, v182
	v_writelane_b32 v250, s11, 28
	s_add_u32 s10, s5, s20
	v_readlane_b32 s5, v251, 44
	s_addc_u32 s11, s5, s21
	v_writelane_b32 v250, s10, 29
	v_readlane_b32 s5, v251, 45
	s_mov_b64 s[20:21], 0
	v_writelane_b32 v250, s11, 30
	s_mov_b32 s10, s40
	v_writelane_b32 v250, s10, 9
	s_nop 1
	v_writelane_b32 v250, s11, 10
	s_lshl_b64 s[10:11], s[40:41], 15
	s_add_u32 s10, s5, s10
	v_readlane_b32 s5, v251, 46
	s_addc_u32 s11, s5, s11
	v_writelane_b32 v250, s10, 31
	s_add_i32 s5, s18, 0xfffffb84
	s_nop 0
	v_writelane_b32 v250, s11, 32
	v_writelane_b32 v250, s62, 33
	v_writelane_b32 v250, s69, 34
	s_mov_b32 s99, 0
	s_branch .LBB0_32

.LBB0_32:
	s_barrier
	s_nop 0
	v_cmp_eq_u32_e64 s[36:37], 0, v128
	s_and_saveexec_b64 s[10:11], s[36:37]
	s_cbranch_execz .LBB0_36
	s_mov_b64 s[24:25], exec
	v_mbcnt_lo_u32_b32 v0, s24, 0
	v_mbcnt_hi_u32_b32 v0, s25, v0
	v_cmp_eq_u32_e32 vcc, 0, v0
	s_and_saveexec_b64 s[18:19], vcc
	s_cbranch_execz .LBB0_35
	s_cmp_lg_u32 s99, 0
	s_cbranch_scc1 .Lpop_pf
	s_bcnt1_i32_b64 s24, s[24:25]
	v_mov_b32_e32 v2, s24
	v_readlane_b32 s24, v250, 11
	v_readlane_b32 s25, v250, 12
	s_nop 4
	global_atomic_add v2, v1, v2, s[24:25] sc0
	s_branch .Lpop_join
.Lpop_pf:
	s_waitcnt vmcnt(0)
	v_mov_b32_e32 v2, v255
	s_mov_b32 s99, 0
.Lpop_join:
.LBB0_35:
	s_or_b64 exec, exec, s[18:19]
	s_mov_b64 s[18:19], src_shared_base
	s_waitcnt vmcnt(0)
	v_readfirstlane_b32 s18, v2
	s_nop 1
	v_add_u32_e32 v0, s18, v0
	s_add_i32 s18, 0, 0x20200
	s_cmp_lg_u32 s18, -1
	s_cselect_b32 s18, s18, 0
	s_cselect_b32 s19, s19, 0
	v_mov_b32_e32 v2, s18
	s_waitcnt lgkmcnt(0)
	v_mov_b32_e32 v3, s19
	flat_store_dword v[2:3], v0 sc0 sc1
	s_waitcnt vmcnt(0)

.LBB0_209:
	s_or_b64 exec, exec, s[48:49]
	v_lshlrev_b32_e32 v0, 10, v129
	v_and_b32_e32 v0, 0x3000, v0
	v_add_u32_e32 v34, v120, v0
	v_ashrrev_i32_e32 v35, 31, v34
	v_lshlrev_b64 v[34:35], 11, v[34:35]
	v_lshlrev_b32_e32 v0, 7, v129
	v_lshl_add_u64 v[34:35], s[70:71], 0, v[34:35]
	v_and_b32_e32 v0, 0x180, v0
	v_lshl_add_u64 v[34:35], v[34:35], 0, v[0:1]
	v_lshlrev_b32_e32 v0, 3, v115
	v_lshl_add_u64 v[36:37], v[34:35], 0, v[0:1]
	s_mov_b64 s[38:39], 0x95c8600
	v_lshl_add_u64 v[34:35], v[36:37], 0, s[38:39]
	v_add_co_u32_e32 v36, vcc, 0x95c8000, v36
	s_nop 1
	v_addc_co_u32_e32 v37, vcc, 0, v37, vcc
	global_load_dwordx2 v[44:45], v[34:35], off
	global_load_dwordx2 v[46:47], v[34:35], off offset:16
	global_load_dwordx2 v[48:49], v[34:35], off offset:32
	global_load_dwordx2 v[50:51], v[34:35], off offset:48
	global_load_dwordx2 v[52:53], v[34:35], off offset:64
	global_load_dwordx2 v[54:55], v[34:35], off offset:80
	global_load_dwordx2 v[56:57], v[34:35], off offset:96
	global_load_dwordx2 v[58:59], v[34:35], off offset:112
	v_readfirstlane_b32 s100, v128
	s_cmp_lg_u32 s100, 0
	s_cbranch_scc1 .Lpf_skip_sb
	v_readlane_b32 s100, v250, 11
	v_readlane_b32 s101, v250, 12
	s_mov_b64 s[38:39], exec
	s_mov_b64 exec, 1
	v_mov_b32_e32 v255, 1
	s_nop 4
	global_atomic_add v255, v1, v255, s[100:101] sc0
	s_mov_b64 exec, s[38:39]
	s_mov_b32 s99, 1
.Lpf_skip_sb:
	s_mov_b32 s38, 0xbfb8aa3b
	s_mov_b32 s39, 0xbfb8aa3b
	s_mov_b32 s48, 1.0
	s_mov_b32 s49, 1.0
	s_waitcnt vmcnt(0)
	v_lshlrev_b32_e32 v64, 16, v44
	v_and_b32_e32 v65, 0xffff0000, v44
	v_lshlrev_b32_e32 v66, 16, v45
	v_and_b32_e32 v67, 0xffff0000, v45
	v_lshlrev_b32_e32 v68, 16, v46
	v_and_b32_e32 v69, 0xffff0000, v46
	v_lshlrev_b32_e32 v70, 16, v47
	v_and_b32_e32 v71, 0xffff0000, v47
	v_lshlrev_b32_e32 v72, 16, v48
	v_and_b32_e32 v73, 0xffff0000, v48
	v_lshlrev_b32_e32 v74, 16, v49
	v_and_b32_e32 v75, 0xffff0000, v49
	v_lshlrev_b32_e32 v76, 16, v50
	v_and_b32_e32 v77, 0xffff0000, v50
	v_lshlrev_b32_e32 v78, 16, v51
	v_and_b32_e32 v79, 0xffff0000, v51
	v_pk_mul_f32 v[80:81], v[64:65], s[38:39]
	v_pk_mul_f32 v[82:83], v[66:67], s[38:39]
	v_pk_mul_f32 v[84:85], v[68:69], s[38:39]
	v_pk_mul_f32 v[86:87], v[70:71], s[38:39]
	v_pk_mul_f32 v[88:89], v[72:73], s[38:39]
	v_pk_mul_f32 v[90:91], v[74:75], s[38:39]
	v_pk_mul_f32 v[92:93], v[76:77], s[38:39]
	v_pk_mul_f32 v[94:95], v[78:79], s[38:39]
	v_exp_f32_e32 v80, v80
	v_exp_f32_e32 v81, v81
	v_exp_f32_e32 v82, v82
	v_exp_f32_e32 v83, v83
	v_exp_f32_e32 v84, v84
	v_exp_f32_e32 v85, v85
	v_exp_f32_e32 v86, v86
	v_exp_f32_e32 v87, v87
	v_exp_f32_e32 v88, v88
	v_exp_f32_e32 v89, v89
	v_exp_f32_e32 v90, v90
	v_exp_f32_e32 v91, v91
	v_exp_f32_e32 v92, v92
	v_exp_f32_e32 v93, v93
	v_exp_f32_e32 v94, v94
	v_exp_f32_e32 v95, v95
	v_pk_add_f32 v[80:81], v[80:81], s[48:49]
	v_pk_add_f32 v[82:83], v[82:83], s[48:49]
	v_pk_add_f32 v[84:85], v[84:85], s[48:49]
	v_pk_add_f32 v[86:87], v[86:87], s[48:49]
	v_pk_add_f32 v[88:89], v[88:89], s[48:49]
	v_pk_add_f32 v[90:91], v[90:91], s[48:49]
	v_pk_add_f32 v[92:93], v[92:93], s[48:49]
	v_pk_add_f32 v[94:95], v[94:95], s[48:49]
	v_rcp_f32_e32 v80, v80
	v_rcp_f32_e32 v81, v81
	v_rcp_f32_e32 v82, v82
	v_rcp_f32_e32 v83, v83
	v_rcp_f32_e32 v84, v84
	v_rcp_f32_e32 v85, v85
	v_rcp_f32_e32 v86, v86
	v_rcp_f32_e32 v87, v87
	v_rcp_f32_e32 v88, v88
	v_rcp_f32_e32 v89, v89
	v_rcp_f32_e32 v90, v90
	v_rcp_f32_e32 v91, v91
	v_rcp_f32_e32 v92, v92
	v_rcp_f32_e32 v93, v93
	v_rcp_f32_e32 v94, v94
	v_rcp_f32_e32 v95, v95
	v_pk_mul_f32 v[80:81], v[80:81], v[64:65]
	v_pk_mul_f32 v[82:83], v[82:83], v[66:67]
	v_pk_mul_f32 v[84:85], v[84:85], v[68:69]
	v_pk_mul_f32 v[86:87], v[86:87], v[70:71]
	v_pk_mul_f32 v[88:89], v[88:89], v[72:73]
	v_pk_mul_f32 v[90:91], v[90:91], v[74:75]
	v_pk_mul_f32 v[92:93], v[92:93], v[76:77]
	v_pk_mul_f32 v[94:95], v[94:95], v[78:79]
	v_pk_mul_f32 v[80:81], v[2:3], v[80:81]
	v_pk_mul_f32 v[82:83], v[4:5], v[82:83]
	v_pk_mul_f32 v[84:85], v[6:7], v[84:85]
	v_pk_mul_f32 v[86:87], v[8:9], v[86:87]
	v_pk_mul_f32 v[88:89], v[10:11], v[88:89]
	v_pk_mul_f32 v[90:91], v[12:13], v[90:91]
	v_pk_mul_f32 v[92:93], v[14:15], v[92:93]
	v_pk_mul_f32 v[94:95], v[16:17], v[94:95]
	v_cvt_pk_bf16_f32 v64, v80, v81
	v_cvt_pk_bf16_f32 v65, v82, v83
	v_cvt_pk_bf16_f32 v66, v84, v85
	v_cvt_pk_bf16_f32 v67, v86, v87
	v_cvt_pk_bf16_f32 v68, v88, v89
	v_cvt_pk_bf16_f32 v69, v90, v91
	v_cvt_pk_bf16_f32 v70, v92, v93
	v_cvt_pk_bf16_f32 v71, v94, v95
	global_store_dwordx2 v[34:35], v[64:65], off
	global_store_dwordx2 v[34:35], v[66:67], off offset:16
	global_store_dwordx2 v[34:35], v[68:69], off offset:32
	global_store_dwordx2 v[34:35], v[70:71], off offset:48
	v_lshlrev_b32_e32 v64, 16, v52
	v_and_b32_e32 v65, 0xffff0000, v52
	v_lshlrev_b32_e32 v66, 16, v53
	v_and_b32_e32 v67, 0xffff0000, v53
	v_lshlrev_b32_e32 v68, 16, v54
	v_and_b32_e32 v69, 0xffff0000, v54
	v_lshlrev_b32_e32 v70, 16, v55
	v_and_b32_e32 v71, 0xffff0000, v55
	v_lshlrev_b32_e32 v72, 16, v56
	v_and_b32_e32 v73, 0xffff0000, v56
	v_lshlrev_b32_e32 v74, 16, v57
	v_and_b32_e32 v75, 0xffff0000, v57
	v_lshlrev_b32_e32 v76, 16, v58
	v_and_b32_e32 v77, 0xffff0000, v58
	v_lshlrev_b32_e32 v78, 16, v59
	v_and_b32_e32 v79, 0xffff0000, v59
	v_pk_mul_f32 v[80:81], v[64:65], s[38:39]
	v_pk_mul_f32 v[82:83], v[66:67], s[38:39]
	v_pk_mul_f32 v[84:85], v[68:69], s[38:39]
	v_pk_mul_f32 v[86:87], v[70:71], s[38:39]
	v_pk_mul_f32 v[88:89], v[72:73], s[38:39]
	v_pk_mul_f32 v[90:91], v[74:75], s[38:39]
	v_pk_mul_f32 v[92:93], v[76:77], s[38:39]
	v_pk_mul_f32 v[94:95], v[78:79], s[38:39]
	v_exp_f32_e32 v80, v80
	v_exp_f32_e32 v81, v81
	v_exp_f32_e32 v82, v82
	v_exp_f32_e32 v83, v83
	v_exp_f32_e32 v84, v84
	v_exp_f32_e32 v85, v85
	v_exp_f32_e32 v86, v86
	v_exp_f32_e32 v87, v87
	v_exp_f32_e32 v88, v88
	v_exp_f32_e32 v89, v89
	v_exp_f32_e32 v90, v90
	v_exp_f32_e32 v91, v91
	v_exp_f32_e32 v92, v92
	v_exp_f32_e32 v93, v93
	v_exp_f32_e32 v94, v94
	v_exp_f32_e32 v95, v95
	v_pk_add_f32 v[80:81], v[80:81], s[48:49]
	v_pk_add_f32 v[82:83], v[82:83], s[48:49]
	v_pk_add_f32 v[84:85], v[84:85], s[48:49]
	v_pk_add_f32 v[86:87], v[86:87], s[48:49]
	v_pk_add_f32 v[88:89], v[88:89], s[48:49]
	v_pk_add_f32 v[90:91], v[90:91], s[48:49]
	v_pk_add_f32 v[92:93], v[92:93], s[48:49]
	v_pk_add_f32 v[94:95], v[94:95], s[48:49]
	v_rcp_f32_e32 v80, v80
	v_rcp_f32_e32 v81, v81
	v_rcp_f32_e32 v82, v82
	v_rcp_f32_e32 v83, v83
	v_rcp_f32_e32 v84, v84
	v_rcp_f32_e32 v85, v85
	v_rcp_f32_e32 v86, v86
	v_rcp_f32_e32 v87, v87
	v_rcp_f32_e32 v88, v88
	v_rcp_f32_e32 v89, v89
	v_rcp_f32_e32 v90, v90
	v_rcp_f32_e32 v91, v91
	v_rcp_f32_e32 v92, v92
	v_rcp_f32_e32 v93, v93
	v_rcp_f32_e32 v94, v94
	v_rcp_f32_e32 v95, v95
	v_pk_mul_f32 v[80:81], v[80:81], v[64:65]
	v_pk_mul_f32 v[82:83], v[82:83], v[66:67]
	v_pk_mul_f32 v[84:85], v[84:85], v[68:69]
	v_pk_mul_f32 v[86:87], v[86:87], v[70:71]
	v_pk_mul_f32 v[88:89], v[88:89], v[72:73]
	v_pk_mul_f32 v[90:91], v[90:91], v[74:75]
	v_pk_mul_f32 v[92:93], v[92:93], v[76:77]
	v_pk_mul_f32 v[94:95], v[94:95], v[78:79]
	v_pk_mul_f32 v[80:81], v[18:19], v[80:81]
	v_pk_mul_f32 v[82:83], v[20:21], v[82:83]
	v_pk_mul_f32 v[84:85], v[22:23], v[84:85]
	v_pk_mul_f32 v[86:87], v[24:25], v[86:87]
	v_pk_mul_f32 v[88:89], v[26:27], v[88:89]
	v_pk_mul_f32 v[90:91], v[28:29], v[90:91]
	v_pk_mul_f32 v[92:93], v[30:31], v[92:93]
	v_pk_mul_f32 v[94:95], v[32:33], v[94:95]
	v_cvt_pk_bf16_f32 v64, v80, v81
	v_cvt_pk_bf16_f32 v65, v82, v83
	v_cvt_pk_bf16_f32 v66, v84, v85
	v_cvt_pk_bf16_f32 v67, v86, v87
	v_cvt_pk_bf16_f32 v68, v88, v89
	v_cvt_pk_bf16_f32 v69, v90, v91
	v_cvt_pk_bf16_f32 v70, v92, v93
	v_cvt_pk_bf16_f32 v71, v94, v95
	global_store_dwordx2 v[34:35], v[64:65], off offset:64
	global_store_dwordx2 v[34:35], v[66:67], off offset:80
	global_store_dwordx2 v[34:35], v[68:69], off offset:96
	global_store_dwordx2 v[34:35], v[70:71], off offset:112
	s_waitcnt lgkmcnt(0)
	s_barrier

.LBB0_257:
	s_or_b64 exec, exec, s[42:43]
	v_xor_b32_e32 v0, 32, v216
	v_add_u32_e32 v2, 64, v113
	v_cmp_lt_i32_e32 vcc, v0, v2
	v_readlane_b32 s38, v251, 27
	v_readlane_b32 s39, v251, 28
	v_cndmask_b32_e32 v0, v216, v0, vcc
	v_lshlrev_b32_e32 v0, 2, v0
	ds_bpermute_b32 v0, v0, v148
	s_waitcnt lgkmcnt(0)
	v_add_f32_e32 v0, v148, v0
	v_rcp_f32_e32 v4, v0
	v_lshlrev_b32_e32 v0, 9, v120
	v_and_b32_e32 v0, 0x3000, v0
	v_add_u32_e32 v2, v112, v0
	v_ashrrev_i32_e32 v3, 31, v2
	v_lshlrev_b64 v[2:3], 11, v[2:3]
	v_lshlrev_b32_e32 v0, 7, v120
	v_lshl_add_u64 v[2:3], s[38:39], 0, v[2:3]
	v_and_b32_e32 v0, 0x380, v0
	v_lshl_add_u64 v[2:3], v[2:3], 0, v[0:1]
	v_lshlrev_b32_e32 v0, 3, v121
	v_lshl_add_u64 v[2:3], v[2:3], 0, v[0:1]
	global_load_dwordx2 v[192:193], v[2:3], off
	global_load_dwordx2 v[194:195], v[2:3], off offset:16
	global_load_dwordx2 v[196:197], v[2:3], off offset:32
	global_load_dwordx2 v[198:199], v[2:3], off offset:48
	global_load_dwordx2 v[200:201], v[2:3], off offset:64
	global_load_dwordx2 v[202:203], v[2:3], off offset:80
	global_load_dwordx2 v[204:205], v[2:3], off offset:96
	global_load_dwordx2 v[206:207], v[2:3], off offset:112
	v_readfirstlane_b32 s100, v128
	s_cmp_lg_u32 s100, 0
	s_cbranch_scc1 .Lpf_skip_fox
	v_readlane_b32 s100, v250, 11
	v_readlane_b32 s101, v250, 12
	s_mov_b64 s[44:45], exec
	s_mov_b64 exec, 1
	v_mov_b32_e32 v255, 1
	s_nop 4
	global_atomic_add v255, v1, v255, s[100:101] sc0
	s_mov_b64 exec, s[44:45]
	s_mov_b32 s99, 1
.Lpf_skip_fox:
	s_mov_b32 s44, 0xbfb8aa3b
	s_mov_b32 s45, 0xbfb8aa3b
	s_mov_b32 s46, 1.0
	s_mov_b32 s47, 1.0
	v_pk_mul_f32 v[32:33], v[32:33], v[4:5] op_sel_hi:[1,0]
	v_pk_mul_f32 v[34:35], v[34:35], v[4:5] op_sel_hi:[1,0]
	v_pk_mul_f32 v[36:37], v[36:37], v[4:5] op_sel_hi:[1,0]
	v_pk_mul_f32 v[38:39], v[38:39], v[4:5] op_sel_hi:[1,0]
	v_pk_mul_f32 v[40:41], v[40:41], v[4:5] op_sel_hi:[1,0]
	v_pk_mul_f32 v[42:43], v[42:43], v[4:5] op_sel_hi:[1,0]
	v_pk_mul_f32 v[44:45], v[44:45], v[4:5] op_sel_hi:[1,0]
	v_pk_mul_f32 v[46:47], v[46:47], v[4:5] op_sel_hi:[1,0]
	v_pk_mul_f32 v[16:17], v[16:17], v[4:5] op_sel_hi:[1,0]
	v_pk_mul_f32 v[18:19], v[18:19], v[4:5] op_sel_hi:[1,0]
	v_pk_mul_f32 v[20:21], v[20:21], v[4:5] op_sel_hi:[1,0]
	v_pk_mul_f32 v[22:23], v[22:23], v[4:5] op_sel_hi:[1,0]
	v_pk_mul_f32 v[24:25], v[24:25], v[4:5] op_sel_hi:[1,0]
	v_pk_mul_f32 v[26:27], v[26:27], v[4:5] op_sel_hi:[1,0]
	v_pk_mul_f32 v[28:29], v[28:29], v[4:5] op_sel_hi:[1,0]
	v_pk_mul_f32 v[30:31], v[30:31], v[4:5] op_sel_hi:[1,0]
	s_waitcnt vmcnt(0)
	v_lshlrev_b32_e32 v64, 16, v192
	v_and_b32_e32 v65, 0xffff0000, v192
	v_lshlrev_b32_e32 v66, 16, v193
	v_and_b32_e32 v67, 0xffff0000, v193
	v_lshlrev_b32_e32 v68, 16, v194
	v_and_b32_e32 v69, 0xffff0000, v194
	v_lshlrev_b32_e32 v70, 16, v195
	v_and_b32_e32 v71, 0xffff0000, v195
	v_lshlrev_b32_e32 v72, 16, v196
	v_and_b32_e32 v73, 0xffff0000, v196
	v_lshlrev_b32_e32 v74, 16, v197
	v_and_b32_e32 v75, 0xffff0000, v197
	v_lshlrev_b32_e32 v76, 16, v198
	v_and_b32_e32 v77, 0xffff0000, v198
	v_lshlrev_b32_e32 v78, 16, v199
	v_and_b32_e32 v79, 0xffff0000, v199
	v_pk_mul_f32 v[80:81], v[64:65], s[44:45]
	v_pk_mul_f32 v[82:83], v[66:67], s[44:45]
	v_pk_mul_f32 v[84:85], v[68:69], s[44:45]
	v_pk_mul_f32 v[86:87], v[70:71], s[44:45]
	v_pk_mul_f32 v[88:89], v[72:73], s[44:45]
	v_pk_mul_f32 v[90:91], v[74:75], s[44:45]
	v_pk_mul_f32 v[92:93], v[76:77], s[44:45]
	v_pk_mul_f32 v[94:95], v[78:79], s[44:45]
	v_exp_f32_e32 v80, v80
	v_exp_f32_e32 v81, v81
	v_exp_f32_e32 v82, v82
	v_exp_f32_e32 v83, v83
	v_exp_f32_e32 v84, v84
	v_exp_f32_e32 v85, v85
	v_exp_f32_e32 v86, v86
	v_exp_f32_e32 v87, v87
	v_exp_f32_e32 v88, v88
	v_exp_f32_e32 v89, v89
	v_exp_f32_e32 v90, v90
	v_exp_f32_e32 v91, v91
	v_exp_f32_e32 v92, v92
	v_exp_f32_e32 v93, v93
	v_exp_f32_e32 v94, v94
	v_exp_f32_e32 v95, v95
	v_pk_add_f32 v[80:81], v[80:81], s[46:47]
	v_pk_add_f32 v[82:83], v[82:83], s[46:47]
	v_pk_add_f32 v[84:85], v[84:85], s[46:47]
	v_pk_add_f32 v[86:87], v[86:87], s[46:47]
	v_pk_add_f32 v[88:89], v[88:89], s[46:47]
	v_pk_add_f32 v[90:91], v[90:91], s[46:47]
	v_pk_add_f32 v[92:93], v[92:93], s[46:47]
	v_pk_add_f32 v[94:95], v[94:95], s[46:47]
	v_rcp_f32_e32 v80, v80
	v_rcp_f32_e32 v81, v81
	v_rcp_f32_e32 v82, v82
	v_rcp_f32_e32 v83, v83
	v_rcp_f32_e32 v84, v84
	v_rcp_f32_e32 v85, v85
	v_rcp_f32_e32 v86, v86
	v_rcp_f32_e32 v87, v87
	v_rcp_f32_e32 v88, v88
	v_rcp_f32_e32 v89, v89
	v_rcp_f32_e32 v90, v90
	v_rcp_f32_e32 v91, v91
	v_rcp_f32_e32 v92, v92
	v_rcp_f32_e32 v93, v93
	v_rcp_f32_e32 v94, v94
	v_rcp_f32_e32 v95, v95
	v_pk_mul_f32 v[80:81], v[80:81], v[64:65]
	v_pk_mul_f32 v[82:83], v[82:83], v[66:67]
	v_pk_mul_f32 v[84:85], v[84:85], v[68:69]
	v_pk_mul_f32 v[86:87], v[86:87], v[70:71]
	v_pk_mul_f32 v[88:89], v[88:89], v[72:73]
	v_pk_mul_f32 v[90:91], v[90:91], v[74:75]
	v_pk_mul_f32 v[92:93], v[92:93], v[76:77]
	v_pk_mul_f32 v[94:95], v[94:95], v[78:79]
	v_pk_mul_f32 v[80:81], v[32:33], v[80:81]
	v_pk_mul_f32 v[82:83], v[34:35], v[82:83]
	v_pk_mul_f32 v[84:85], v[36:37], v[84:85]
	v_pk_mul_f32 v[86:87], v[38:39], v[86:87]
	v_pk_mul_f32 v[88:89], v[40:41], v[88:89]
	v_pk_mul_f32 v[90:91], v[42:43], v[90:91]
	v_pk_mul_f32 v[92:93], v[44:45], v[92:93]
	v_pk_mul_f32 v[94:95], v[46:47], v[94:95]
	v_cvt_pk_bf16_f32 v64, v80, v81
	v_cvt_pk_bf16_f32 v65, v82, v83
	v_cvt_pk_bf16_f32 v66, v84, v85
	v_cvt_pk_bf16_f32 v67, v86, v87
	v_cvt_pk_bf16_f32 v68, v88, v89
	v_cvt_pk_bf16_f32 v69, v90, v91
	v_cvt_pk_bf16_f32 v70, v92, v93
	v_cvt_pk_bf16_f32 v71, v94, v95
	global_store_dwordx2 v[2:3], v[64:65], off
	global_store_dwordx2 v[2:3], v[66:67], off offset:16
	global_store_dwordx2 v[2:3], v[68:69], off offset:32
	global_store_dwordx2 v[2:3], v[70:71], off offset:48
	v_lshlrev_b32_e32 v64, 16, v200
	v_and_b32_e32 v65, 0xffff0000, v200
	v_lshlrev_b32_e32 v66, 16, v201
	v_and_b32_e32 v67, 0xffff0000, v201
	v_lshlrev_b32_e32 v68, 16, v202
	v_and_b32_e32 v69, 0xffff0000, v202
	v_lshlrev_b32_e32 v70, 16, v203
	v_and_b32_e32 v71, 0xffff0000, v203
	v_lshlrev_b32_e32 v72, 16, v204
	v_and_b32_e32 v73, 0xffff0000, v204
	v_lshlrev_b32_e32 v74, 16, v205
	v_and_b32_e32 v75, 0xffff0000, v205
	v_lshlrev_b32_e32 v76, 16, v206
	v_and_b32_e32 v77, 0xffff0000, v206
	v_lshlrev_b32_e32 v78, 16, v207
	v_and_b32_e32 v79, 0xffff0000, v207
	v_pk_mul_f32 v[80:81], v[64:65], s[44:45]
	v_pk_mul_f32 v[82:83], v[66:67], s[44:45]
	v_pk_mul_f32 v[84:85], v[68:69], s[44:45]
	v_pk_mul_f32 v[86:87], v[70:71], s[44:45]
	v_pk_mul_f32 v[88:89], v[72:73], s[44:45]
	v_pk_mul_f32 v[90:91], v[74:75], s[44:45]
	v_pk_mul_f32 v[92:93], v[76:77], s[44:45]
	v_pk_mul_f32 v[94:95], v[78:79], s[44:45]
	v_exp_f32_e32 v80, v80
	v_exp_f32_e32 v81, v81
	v_exp_f32_e32 v82, v82
	v_exp_f32_e32 v83, v83
	v_exp_f32_e32 v84, v84
	v_exp_f32_e32 v85, v85
	v_exp_f32_e32 v86, v86
	v_exp_f32_e32 v87, v87
	v_exp_f32_e32 v88, v88
	v_exp_f32_e32 v89, v89
	v_exp_f32_e32 v90, v90
	v_exp_f32_e32 v91, v91
	v_exp_f32_e32 v92, v92
	v_exp_f32_e32 v93, v93
	v_exp_f32_e32 v94, v94
	v_exp_f32_e32 v95, v95
	v_pk_add_f32 v[80:81], v[80:81], s[46:47]
	v_pk_add_f32 v[82:83], v[82:83], s[46:47]
	v_pk_add_f32 v[84:85], v[84:85], s[46:47]
	v_pk_add_f32 v[86:87], v[86:87], s[46:47]
	v_pk_add_f32 v[88:89], v[88:89], s[46:47]
	v_pk_add_f32 v[90:91], v[90:91], s[46:47]
	v_pk_add_f32 v[92:93], v[92:93], s[46:47]
	v_pk_add_f32 v[94:95], v[94:95], s[46:47]
	v_rcp_f32_e32 v80, v80
	v_rcp_f32_e32 v81, v81
	v_rcp_f32_e32 v82, v82
	v_rcp_f32_e32 v83, v83
	v_rcp_f32_e32 v84, v84
	v_rcp_f32_e32 v85, v85
	v_rcp_f32_e32 v86, v86
	v_rcp_f32_e32 v87, v87
	v_rcp_f32_e32 v88, v88
	v_rcp_f32_e32 v89, v89
	v_rcp_f32_e32 v90, v90
	v_rcp_f32_e32 v91, v91
	v_rcp_f32_e32 v92, v92
	v_rcp_f32_e32 v93, v93
	v_rcp_f32_e32 v94, v94
	v_rcp_f32_e32 v95, v95
	v_pk_mul_f32 v[80:81], v[80:81], v[64:65]
	v_pk_mul_f32 v[82:83], v[82:83], v[66:67]
	v_pk_mul_f32 v[84:85], v[84:85], v[68:69]
	v_pk_mul_f32 v[86:87], v[86:87], v[70:71]
	v_pk_mul_f32 v[88:89], v[88:89], v[72:73]
	v_pk_mul_f32 v[90:91], v[90:91], v[74:75]
	v_pk_mul_f32 v[92:93], v[92:93], v[76:77]
	v_pk_mul_f32 v[94:95], v[94:95], v[78:79]
	v_pk_mul_f32 v[80:81], v[16:17], v[80:81]
	v_pk_mul_f32 v[82:83], v[18:19], v[82:83]
	v_pk_mul_f32 v[84:85], v[20:21], v[84:85]
	v_pk_mul_f32 v[86:87], v[22:23], v[86:87]
	v_pk_mul_f32 v[88:89], v[24:25], v[88:89]
	v_pk_mul_f32 v[90:91], v[26:27], v[90:91]
	v_pk_mul_f32 v[92:93], v[28:29], v[92:93]
	v_pk_mul_f32 v[94:95], v[30:31], v[94:95]
	v_cvt_pk_bf16_f32 v64, v80, v81
	v_cvt_pk_bf16_f32 v65, v82, v83
	v_cvt_pk_bf16_f32 v66, v84, v85
	v_cvt_pk_bf16_f32 v67, v86, v87
	v_cvt_pk_bf16_f32 v68, v88, v89
	v_cvt_pk_bf16_f32 v69, v90, v91
	v_cvt_pk_bf16_f32 v70, v92, v93
	v_cvt_pk_bf16_f32 v71, v94, v95
	global_store_dwordx2 v[2:3], v[64:65], off offset:64
	global_store_dwordx2 v[2:3], v[66:67], off offset:80
	global_store_dwordx2 v[2:3], v[68:69], off offset:96
	global_store_dwordx2 v[2:3], v[70:71], off offset:112
